# out-GEMM residual/norm epilogue also software-pipelined in quarters (on top of the quarter-pipelined down epilogue)
# baseline (speedup 1.0000x reference)
; #define EPI_COL(u) (EPI_CB(u) + 8 * fq)
; DI u32x4 pack8(const float* v) { u32x4 w; w.x = pk2(v[0], v[1]); w.y = pk2(v[2], v[3]); w.z = pk2(v[4], v[5]); w.w = pk2(v[6], v[7]); return w; }
;     DI void operator()(const Acc& acc, const Unit& u, int wr, int wc, int fr, int fq) const {
; #pragma unroll
;         for (int ai = 0; ai < 2; ++ai)
; #pragma unroll
;             for (int m = 0; m < 4; ++m) {
;                 const int row = EPI_ROW(u); float part = 0.f;
; #pragma unroll
;                 for (int bj = 0; bj < 2; ++bj) {
;                     const int col = EPI_COL(u);
;                     const float* rp = res + (size_t)row * 1024 + col; float* op = out + (size_t)row * 1024 + col;
;                     const f32x4 o0 = *(const f32x4*)rp + acc[ai][bj][m][0], o1 = *(const f32x4*)(rp + 4) + acc[ai][bj][m][1];
;                     *(f32x4*)op = o0; *(f32x4*)(op + 4) = o1;
;                     part += o0[0] * o0[0] + o0[1] * o0[1] + o0[2] * o0[2] + o0[3] * o0[3] + o1[0] * o1[0] + o1[1] * o1[1] + o1[2] * o1[2] + o1[3] * o1[3];
;                     const float v[8] = {o0[0], o0[1], o0[2], o0[3], o1[0], o1[1], o1[2], o1[3]};
;                     *(u32x4*)(xb + (size_t)row * 1024 + col) = pack8(v);
;                 }
;                 part += __shfl_xor(part, 16); part += __shfl_xor(part, 32);
;                 if (fq == 0) atomicAdd(rss + row, part);
.LBB0_1299:
	v_and_b32_e32 v242, 64, v233
	v_xor_b32_e32 v241, 16, v233
	v_add_u32_e32 v243, 64, v242
	v_cmp_lt_i32_e32 vcc, v241, v243
	s_lshl_b32 s2, s54, 8
	v_cndmask_b32_e32 v241, v233, v241, vcc
	s_add_i32 s2, s2, s86
	v_lshlrev_b32_e32 v242, 2, v241
	v_xor_b32_e32 v241, 32, v233
	v_cmp_lt_i32_e32 vcc, v241, v243
	v_add_u32_e32 v240, s2, v146
	s_lshl_b32 s2, s50, 8
	s_or_b32 s2, s2, s87
	v_cndmask_b32_e32 v241, v233, v241, vcc
	v_lshlrev_b32_e32 v243, 2, v241
	v_lshl_add_u32 v241, v147, 3, s2
	v_cmp_eq_u32_e32 vcc, 0, v147
	v_lshlrev_b32_e32 v186, 12, v240
	v_lshl_add_u32 v186, v241, 2, v186
	v_lshrrev_b32_e32 v187, 1, v186
	v_and_b32_e32 v230, 8, v233
	v_mul_u32_u24_e32 v230, 0xffe, v230
	v_sub_u32_e32 v186, v186, v230
	v_add_u32_e32 v230, 0x0, v186
	v_add_u32_e32 v231, 0x8000, v186
	global_load_dwordx4 v[138:141], v230, s[20:21]
	global_load_dwordx4 v[142:145], v231, s[20:21]
	global_load_dwordx4 v[150:153], v230, s[20:21] offset:512
	global_load_dwordx4 v[154:157], v231, s[20:21] offset:512
	v_add_u32_e32 v230, 0x10000, v186
	v_add_u32_e32 v231, 0x18000, v186
	global_load_dwordx4 v[158:161], v230, s[20:21]
	global_load_dwordx4 v[162:165], v231, s[20:21]
	global_load_dwordx4 v[166:169], v230, s[20:21] offset:512
	global_load_dwordx4 v[170:173], v231, s[20:21] offset:512
	v_add_u32_e32 v230, 0x20000, v186
	v_add_u32_e32 v231, 0x28000, v186
	global_load_dwordx4 v[174:177], v230, s[20:21]
	global_load_dwordx4 v[178:181], v231, s[20:21]
	global_load_dwordx4 v[182:185], v230, s[20:21] offset:512
	global_load_dwordx4 v[210:213], v231, s[20:21] offset:512
	v_add_u32_e32 v230, 0x30000, v186
	v_add_u32_e32 v231, 0x38000, v186
	global_load_dwordx4 v[214:217], v230, s[20:21]
	global_load_dwordx4 v[218:221], v231, s[20:21]
	global_load_dwordx4 v[222:225], v230, s[20:21] offset:512
	global_load_dwordx4 v[226:229], v231, s[20:21] offset:512
	s_waitcnt vmcnt(8)
	v_mov_b32_e32 v244, v138
	v_mov_b32_e32 v245, v139
	v_mov_b32_e32 v246, v140
	v_mov_b32_e32 v247, v141
	v_mov_b32_dpp v138, v142 row_ror:8 row_mask:0xf bank_mask:0xc
	v_mov_b32_dpp v139, v143 row_ror:8 row_mask:0xf bank_mask:0xc
	v_mov_b32_dpp v140, v144 row_ror:8 row_mask:0xf bank_mask:0xc
	v_mov_b32_dpp v141, v145 row_ror:8 row_mask:0xf bank_mask:0xc
	v_mov_b32_dpp v142, v244 row_ror:8 row_mask:0xf bank_mask:0x3
	v_mov_b32_dpp v143, v245 row_ror:8 row_mask:0xf bank_mask:0x3
	v_mov_b32_dpp v144, v246 row_ror:8 row_mask:0xf bank_mask:0x3
	v_mov_b32_dpp v145, v247 row_ror:8 row_mask:0xf bank_mask:0x3
	v_pk_add_f32 v[124:125], v[124:125], v[138:139]
	v_pk_add_f32 v[126:127], v[126:127], v[140:141]
	v_pk_add_f32 v[120:121], v[120:121], v[142:143]
	v_pk_add_f32 v[122:123], v[122:123], v[144:145]
	v_mul_f32_e32 v235, v124, v124
	v_fmac_f32_e32 v235, v125, v125
	v_fmac_f32_e32 v235, v126, v126
	v_fmac_f32_e32 v235, v127, v127
	v_fmac_f32_e32 v235, v120, v120
	v_fmac_f32_e32 v235, v121, v121
	v_fmac_f32_e32 v235, v122, v122
	v_fmac_f32_e32 v235, v123, v123
	v_cvt_pk_bf16_f32 v138, v124, v125
	v_cvt_pk_bf16_f32 v139, v126, v127
	v_cvt_pk_bf16_f32 v140, v120, v121
	v_cvt_pk_bf16_f32 v141, v122, v123
	v_add_u32_e32 v234, 0x0, v187
	global_store_dwordx4 v234, v[138:141], s[26:27]
	v_mov_b32_e32 v244, v120
	v_mov_b32_e32 v245, v121
	v_mov_b32_e32 v246, v122
	v_mov_b32_e32 v247, v123
	v_mov_b32_dpp v120, v124 row_ror:8 row_mask:0xf bank_mask:0x3
	v_mov_b32_dpp v121, v125 row_ror:8 row_mask:0xf bank_mask:0x3
	v_mov_b32_dpp v122, v126 row_ror:8 row_mask:0xf bank_mask:0x3
	v_mov_b32_dpp v123, v127 row_ror:8 row_mask:0xf bank_mask:0x3
	v_mov_b32_dpp v124, v244 row_ror:8 row_mask:0xf bank_mask:0xc
	v_mov_b32_dpp v125, v245 row_ror:8 row_mask:0xf bank_mask:0xc
	v_mov_b32_dpp v126, v246 row_ror:8 row_mask:0xf bank_mask:0xc
	v_mov_b32_dpp v127, v247 row_ror:8 row_mask:0xf bank_mask:0xc
	v_add_u32_e32 v230, 0x0, v186
	v_add_u32_e32 v231, 0x8000, v186
	global_store_dwordx4 v230, v[124:127], s[24:25]
	global_store_dwordx4 v231, v[120:123], s[24:25]
	v_mov_b32_e32 v244, v150
	v_mov_b32_e32 v245, v151
	v_mov_b32_e32 v246, v152
	v_mov_b32_e32 v247, v153
	v_mov_b32_dpp v150, v154 row_ror:8 row_mask:0xf bank_mask:0xc
	v_mov_b32_dpp v151, v155 row_ror:8 row_mask:0xf bank_mask:0xc
	v_mov_b32_dpp v152, v156 row_ror:8 row_mask:0xf bank_mask:0xc
	v_mov_b32_dpp v153, v157 row_ror:8 row_mask:0xf bank_mask:0xc
	v_mov_b32_dpp v154, v244 row_ror:8 row_mask:0xf bank_mask:0x3
	v_mov_b32_dpp v155, v245 row_ror:8 row_mask:0xf bank_mask:0x3
	v_mov_b32_dpp v156, v246 row_ror:8 row_mask:0xf bank_mask:0x3
	v_mov_b32_dpp v157, v247 row_ror:8 row_mask:0xf bank_mask:0x3
	v_pk_add_f32 v[116:117], v[116:117], v[150:151]
	v_pk_add_f32 v[118:119], v[118:119], v[152:153]
	v_pk_add_f32 v[112:113], v[112:113], v[154:155]
	v_pk_add_f32 v[114:115], v[114:115], v[156:157]
	v_fmac_f32_e32 v235, v116, v116
	v_fmac_f32_e32 v235, v117, v117
	v_fmac_f32_e32 v235, v118, v118
	v_fmac_f32_e32 v235, v119, v119
	v_fmac_f32_e32 v235, v112, v112
	v_fmac_f32_e32 v235, v113, v113
	v_fmac_f32_e32 v235, v114, v114
	v_fmac_f32_e32 v235, v115, v115
	v_cvt_pk_bf16_f32 v150, v116, v117
	v_cvt_pk_bf16_f32 v151, v118, v119
	v_cvt_pk_bf16_f32 v152, v112, v113
	v_cvt_pk_bf16_f32 v153, v114, v115
	global_store_dwordx4 v234, v[150:153], s[26:27] offset:256
	v_mov_b32_e32 v244, v112
	v_mov_b32_e32 v245, v113
	v_mov_b32_e32 v246, v114
	v_mov_b32_e32 v247, v115
	v_mov_b32_dpp v112, v116 row_ror:8 row_mask:0xf bank_mask:0x3
	v_mov_b32_dpp v113, v117 row_ror:8 row_mask:0xf bank_mask:0x3
	v_mov_b32_dpp v114, v118 row_ror:8 row_mask:0xf bank_mask:0x3
	v_mov_b32_dpp v115, v119 row_ror:8 row_mask:0xf bank_mask:0x3
	v_mov_b32_dpp v116, v244 row_ror:8 row_mask:0xf bank_mask:0xc
; #define EPI_COL(u) (EPI_CB(u) + 8 * fq)
; DI u32x4 pack8(const float* v) { u32x4 w; w.x = pk2(v[0], v[1]); w.y = pk2(v[2], v[3]); w.z = pk2(v[4], v[5]); w.w = pk2(v[6], v[7]); return w; }
;     DI void operator()(const Acc& acc, const Unit& u, int wr, int wc, int fr, int fq) const {
;     ...
;             for (int m = 0; m < 4; ++m) {
;                 const int row = EPI_ROW(u); float part = 0.f;
; #pragma unroll
;                 for (int bj = 0; bj < 2; ++bj) {
;                     const int col = EPI_COL(u);
;                     const float* rp = res + (size_t)row * 1024 + col; float* op = out + (size_t)row * 1024 + col;
;                     const f32x4 o0 = *(const f32x4*)rp + acc[ai][bj][m][0], o1 = *(const f32x4*)(rp + 4) + acc[ai][bj][m][1];
;                     *(f32x4*)op = o0; *(f32x4*)(op + 4) = o1;
;                     part += o0[0] * o0[0] + o0[1] * o0[1] + o0[2] * o0[2] + o0[3] * o0[3] + o1[0] * o1[0] + o1[1] * o1[1] + o1[2] * o1[2] + o1[3] * o1[3];
;                     const float v[8] = {o0[0], o0[1], o0[2], o0[3], o1[0], o1[1], o1[2], o1[3]};
;                     *(u32x4*)(xb + (size_t)row * 1024 + col) = pack8(v);
;                 }
	v_mov_b32_dpp v117, v245 row_ror:8 row_mask:0xf bank_mask:0xc
	v_mov_b32_dpp v118, v246 row_ror:8 row_mask:0xf bank_mask:0xc
	v_mov_b32_dpp v119, v247 row_ror:8 row_mask:0xf bank_mask:0xc
	global_store_dwordx4 v230, v[116:119], s[24:25] offset:512
	global_store_dwordx4 v231, v[112:115], s[24:25] offset:512
	v_mov_b32_e32 v244, v158
	v_mov_b32_e32 v245, v159
	v_mov_b32_e32 v246, v160
	v_mov_b32_e32 v247, v161
	v_mov_b32_dpp v158, v162 row_ror:8 row_mask:0xf bank_mask:0xc
	v_mov_b32_dpp v159, v163 row_ror:8 row_mask:0xf bank_mask:0xc
	v_mov_b32_dpp v160, v164 row_ror:8 row_mask:0xf bank_mask:0xc
	v_mov_b32_dpp v161, v165 row_ror:8 row_mask:0xf bank_mask:0xc
	v_mov_b32_dpp v162, v244 row_ror:8 row_mask:0xf bank_mask:0x3
	v_mov_b32_dpp v163, v245 row_ror:8 row_mask:0xf bank_mask:0x3
	v_mov_b32_dpp v164, v246 row_ror:8 row_mask:0xf bank_mask:0x3
	v_mov_b32_dpp v165, v247 row_ror:8 row_mask:0xf bank_mask:0x3
	v_pk_add_f32 v[108:109], v[108:109], v[158:159]
	v_pk_add_f32 v[110:111], v[110:111], v[160:161]
	v_pk_add_f32 v[104:105], v[104:105], v[162:163]
	v_pk_add_f32 v[106:107], v[106:107], v[164:165]
	v_mul_f32_e32 v236, v108, v108
	v_fmac_f32_e32 v236, v109, v109
	v_fmac_f32_e32 v236, v110, v110
	v_fmac_f32_e32 v236, v111, v111
	v_fmac_f32_e32 v236, v104, v104
	v_fmac_f32_e32 v236, v105, v105
	v_fmac_f32_e32 v236, v106, v106
	v_fmac_f32_e32 v236, v107, v107
	v_cvt_pk_bf16_f32 v158, v108, v109
	v_cvt_pk_bf16_f32 v159, v110, v111
	v_cvt_pk_bf16_f32 v160, v104, v105
	v_cvt_pk_bf16_f32 v161, v106, v107
	v_add_u32_e32 v234, 0x8000, v187
	global_store_dwordx4 v234, v[158:161], s[26:27]
	v_mov_b32_e32 v244, v104
	v_mov_b32_e32 v245, v105
	v_mov_b32_e32 v246, v106
	v_mov_b32_e32 v247, v107
	v_mov_b32_dpp v104, v108 row_ror:8 row_mask:0xf bank_mask:0x3
	v_mov_b32_dpp v105, v109 row_ror:8 row_mask:0xf bank_mask:0x3
	v_mov_b32_dpp v106, v110 row_ror:8 row_mask:0xf bank_mask:0x3
	v_mov_b32_dpp v107, v111 row_ror:8 row_mask:0xf bank_mask:0x3
	v_mov_b32_dpp v108, v244 row_ror:8 row_mask:0xf bank_mask:0xc
	v_mov_b32_dpp v109, v245 row_ror:8 row_mask:0xf bank_mask:0xc
	v_mov_b32_dpp v110, v246 row_ror:8 row_mask:0xf bank_mask:0xc
	v_mov_b32_dpp v111, v247 row_ror:8 row_mask:0xf bank_mask:0xc
	v_add_u32_e32 v230, 0x10000, v186
	v_add_u32_e32 v231, 0x18000, v186
	global_store_dwordx4 v230, v[108:111], s[24:25]
	global_store_dwordx4 v231, v[104:107], s[24:25]
	v_mov_b32_e32 v244, v166
	v_mov_b32_e32 v245, v167
	v_mov_b32_e32 v246, v168
	v_mov_b32_e32 v247, v169
	v_mov_b32_dpp v166, v170 row_ror:8 row_mask:0xf bank_mask:0xc
	v_mov_b32_dpp v167, v171 row_ror:8 row_mask:0xf bank_mask:0xc
	v_mov_b32_dpp v168, v172 row_ror:8 row_mask:0xf bank_mask:0xc
	v_mov_b32_dpp v169, v173 row_ror:8 row_mask:0xf bank_mask:0xc
	v_mov_b32_dpp v170, v244 row_ror:8 row_mask:0xf bank_mask:0x3
	v_mov_b32_dpp v171, v245 row_ror:8 row_mask:0xf bank_mask:0x3
	v_mov_b32_dpp v172, v246 row_ror:8 row_mask:0xf bank_mask:0x3
	v_mov_b32_dpp v173, v247 row_ror:8 row_mask:0xf bank_mask:0x3
	v_pk_add_f32 v[100:101], v[100:101], v[166:167]
	v_pk_add_f32 v[102:103], v[102:103], v[168:169]
	v_pk_add_f32 v[96:97], v[96:97], v[170:171]
	v_pk_add_f32 v[98:99], v[98:99], v[172:173]
	v_fmac_f32_e32 v236, v100, v100
	v_fmac_f32_e32 v236, v101, v101
	v_fmac_f32_e32 v236, v102, v102
	v_fmac_f32_e32 v236, v103, v103
	v_fmac_f32_e32 v236, v96, v96
	v_fmac_f32_e32 v236, v97, v97
	v_fmac_f32_e32 v236, v98, v98
	v_fmac_f32_e32 v236, v99, v99
	v_cvt_pk_bf16_f32 v166, v100, v101
	v_cvt_pk_bf16_f32 v167, v102, v103
	v_cvt_pk_bf16_f32 v168, v96, v97
	v_cvt_pk_bf16_f32 v169, v98, v99
	global_store_dwordx4 v234, v[166:169], s[26:27] offset:256
	v_mov_b32_e32 v244, v96
	v_mov_b32_e32 v245, v97
	v_mov_b32_e32 v246, v98
	v_mov_b32_e32 v247, v99
	v_mov_b32_dpp v96, v100 row_ror:8 row_mask:0xf bank_mask:0x3
	v_mov_b32_dpp v97, v101 row_ror:8 row_mask:0xf bank_mask:0x3
	v_mov_b32_dpp v98, v102 row_ror:8 row_mask:0xf bank_mask:0x3
	v_mov_b32_dpp v99, v103 row_ror:8 row_mask:0xf bank_mask:0x3
	v_mov_b32_dpp v100, v244 row_ror:8 row_mask:0xf bank_mask:0xc
	v_mov_b32_dpp v101, v245 row_ror:8 row_mask:0xf bank_mask:0xc
	v_mov_b32_dpp v102, v246 row_ror:8 row_mask:0xf bank_mask:0xc
	v_mov_b32_dpp v103, v247 row_ror:8 row_mask:0xf bank_mask:0xc
	global_store_dwordx4 v230, v[100:103], s[24:25] offset:512
	global_store_dwordx4 v231, v[96:99], s[24:25] offset:512
	v_add_u32_e32 v230, 0x80000, v186
	v_add_u32_e32 v231, 0x88000, v186
	global_load_dwordx4 v[138:141], v230, s[20:21]
	global_load_dwordx4 v[142:145], v231, s[20:21]
	global_load_dwordx4 v[150:153], v230, s[20:21] offset:512
	global_load_dwordx4 v[154:157], v231, s[20:21] offset:512
	v_add_u32_e32 v230, 0x90000, v186
	v_add_u32_e32 v231, 0x98000, v186
	global_load_dwordx4 v[158:161], v230, s[20:21]
	global_load_dwordx4 v[162:165], v231, s[20:21]
	global_load_dwordx4 v[166:169], v230, s[20:21] offset:512
	global_load_dwordx4 v[170:173], v231, s[20:21] offset:512
	s_waitcnt vmcnt(20)
; #define EPI_COL(u) (EPI_CB(u) + 8 * fq)
; DI u32x4 pack8(const float* v) { u32x4 w; w.x = pk2(v[0], v[1]); w.y = pk2(v[2], v[3]); w.z = pk2(v[4], v[5]); w.w = pk2(v[6], v[7]); return w; }
;     DI void operator()(const Acc& acc, const Unit& u, int wr, int wc, int fr, int fq) const {
;     ...
;             for (int m = 0; m < 4; ++m) {
;                 const int row = EPI_ROW(u); float part = 0.f;
; #pragma unroll
;                 for (int bj = 0; bj < 2; ++bj) {
;                     const int col = EPI_COL(u);
;                     const float* rp = res + (size_t)row * 1024 + col; float* op = out + (size_t)row * 1024 + col;
;                     const f32x4 o0 = *(const f32x4*)rp + acc[ai][bj][m][0], o1 = *(const f32x4*)(rp + 4) + acc[ai][bj][m][1];
;                     *(f32x4*)op = o0; *(f32x4*)(op + 4) = o1;
;                     part += o0[0] * o0[0] + o0[1] * o0[1] + o0[2] * o0[2] + o0[3] * o0[3] + o1[0] * o1[0] + o1[1] * o1[1] + o1[2] * o1[2] + o1[3] * o1[3];
;                     const float v[8] = {o0[0], o0[1], o0[2], o0[3], o1[0], o1[1], o1[2], o1[3]};
;                     *(u32x4*)(xb + (size_t)row * 1024 + col) = pack8(v);
;                 }
	v_mov_b32_e32 v244, v174
	v_mov_b32_e32 v245, v175
	v_mov_b32_e32 v246, v176
	v_mov_b32_e32 v247, v177
	v_mov_b32_dpp v174, v178 row_ror:8 row_mask:0xf bank_mask:0xc
	v_mov_b32_dpp v175, v179 row_ror:8 row_mask:0xf bank_mask:0xc
	v_mov_b32_dpp v176, v180 row_ror:8 row_mask:0xf bank_mask:0xc
	v_mov_b32_dpp v177, v181 row_ror:8 row_mask:0xf bank_mask:0xc
	v_mov_b32_dpp v178, v244 row_ror:8 row_mask:0xf bank_mask:0x3
	v_mov_b32_dpp v179, v245 row_ror:8 row_mask:0xf bank_mask:0x3
	v_mov_b32_dpp v180, v246 row_ror:8 row_mask:0xf bank_mask:0x3
	v_mov_b32_dpp v181, v247 row_ror:8 row_mask:0xf bank_mask:0x3
	v_pk_add_f32 v[92:93], v[92:93], v[174:175]
	v_pk_add_f32 v[94:95], v[94:95], v[176:177]
	v_pk_add_f32 v[88:89], v[88:89], v[178:179]
	v_pk_add_f32 v[90:91], v[90:91], v[180:181]
	v_mul_f32_e32 v237, v92, v92
	v_fmac_f32_e32 v237, v93, v93
	v_fmac_f32_e32 v237, v94, v94
	v_fmac_f32_e32 v237, v95, v95
	v_fmac_f32_e32 v237, v88, v88
	v_fmac_f32_e32 v237, v89, v89
	v_fmac_f32_e32 v237, v90, v90
	v_fmac_f32_e32 v237, v91, v91
	v_cvt_pk_bf16_f32 v174, v92, v93
	v_cvt_pk_bf16_f32 v175, v94, v95
	v_cvt_pk_bf16_f32 v176, v88, v89
	v_cvt_pk_bf16_f32 v177, v90, v91
	v_add_u32_e32 v234, 0x10000, v187
	global_store_dwordx4 v234, v[174:177], s[26:27]
	v_mov_b32_e32 v244, v88
	v_mov_b32_e32 v245, v89
	v_mov_b32_e32 v246, v90
	v_mov_b32_e32 v247, v91
	v_mov_b32_dpp v88, v92 row_ror:8 row_mask:0xf bank_mask:0x3
	v_mov_b32_dpp v89, v93 row_ror:8 row_mask:0xf bank_mask:0x3
	v_mov_b32_dpp v90, v94 row_ror:8 row_mask:0xf bank_mask:0x3
	v_mov_b32_dpp v91, v95 row_ror:8 row_mask:0xf bank_mask:0x3
	v_mov_b32_dpp v92, v244 row_ror:8 row_mask:0xf bank_mask:0xc
	v_mov_b32_dpp v93, v245 row_ror:8 row_mask:0xf bank_mask:0xc
	v_mov_b32_dpp v94, v246 row_ror:8 row_mask:0xf bank_mask:0xc
	v_mov_b32_dpp v95, v247 row_ror:8 row_mask:0xf bank_mask:0xc
	v_add_u32_e32 v230, 0x20000, v186
	v_add_u32_e32 v231, 0x28000, v186
	global_store_dwordx4 v230, v[92:95], s[24:25]
	global_store_dwordx4 v231, v[88:91], s[24:25]
	v_mov_b32_e32 v244, v182
	v_mov_b32_e32 v245, v183
	v_mov_b32_e32 v246, v184
	v_mov_b32_e32 v247, v185
	v_mov_b32_dpp v182, v210 row_ror:8 row_mask:0xf bank_mask:0xc
	v_mov_b32_dpp v183, v211 row_ror:8 row_mask:0xf bank_mask:0xc
	v_mov_b32_dpp v184, v212 row_ror:8 row_mask:0xf bank_mask:0xc
	v_mov_b32_dpp v185, v213 row_ror:8 row_mask:0xf bank_mask:0xc
	v_mov_b32_dpp v210, v244 row_ror:8 row_mask:0xf bank_mask:0x3
	v_mov_b32_dpp v211, v245 row_ror:8 row_mask:0xf bank_mask:0x3
	v_mov_b32_dpp v212, v246 row_ror:8 row_mask:0xf bank_mask:0x3
	v_mov_b32_dpp v213, v247 row_ror:8 row_mask:0xf bank_mask:0x3
	v_pk_add_f32 v[84:85], v[84:85], v[182:183]
	v_pk_add_f32 v[86:87], v[86:87], v[184:185]
	v_pk_add_f32 v[80:81], v[80:81], v[210:211]
	v_pk_add_f32 v[82:83], v[82:83], v[212:213]
	v_fmac_f32_e32 v237, v84, v84
	v_fmac_f32_e32 v237, v85, v85
	v_fmac_f32_e32 v237, v86, v86
	v_fmac_f32_e32 v237, v87, v87
	v_fmac_f32_e32 v237, v80, v80
	v_fmac_f32_e32 v237, v81, v81
	v_fmac_f32_e32 v237, v82, v82
	v_fmac_f32_e32 v237, v83, v83
	v_cvt_pk_bf16_f32 v182, v84, v85
	v_cvt_pk_bf16_f32 v183, v86, v87
	v_cvt_pk_bf16_f32 v184, v80, v81
	v_cvt_pk_bf16_f32 v185, v82, v83
	global_store_dwordx4 v234, v[182:185], s[26:27] offset:256
	v_mov_b32_e32 v244, v80
	v_mov_b32_e32 v245, v81
	v_mov_b32_e32 v246, v82
	v_mov_b32_e32 v247, v83
	v_mov_b32_dpp v80, v84 row_ror:8 row_mask:0xf bank_mask:0x3
	v_mov_b32_dpp v81, v85 row_ror:8 row_mask:0xf bank_mask:0x3
	v_mov_b32_dpp v82, v86 row_ror:8 row_mask:0xf bank_mask:0x3
	v_mov_b32_dpp v83, v87 row_ror:8 row_mask:0xf bank_mask:0x3
	v_mov_b32_dpp v84, v244 row_ror:8 row_mask:0xf bank_mask:0xc
	v_mov_b32_dpp v85, v245 row_ror:8 row_mask:0xf bank_mask:0xc
	v_mov_b32_dpp v86, v246 row_ror:8 row_mask:0xf bank_mask:0xc
	v_mov_b32_dpp v87, v247 row_ror:8 row_mask:0xf bank_mask:0xc
	global_store_dwordx4 v230, v[84:87], s[24:25] offset:512
	global_store_dwordx4 v231, v[80:83], s[24:25] offset:512
	v_mov_b32_e32 v244, v214
	v_mov_b32_e32 v245, v215
	v_mov_b32_e32 v246, v216
	v_mov_b32_e32 v247, v217
	v_mov_b32_dpp v214, v218 row_ror:8 row_mask:0xf bank_mask:0xc
	v_mov_b32_dpp v215, v219 row_ror:8 row_mask:0xf bank_mask:0xc
	v_mov_b32_dpp v216, v220 row_ror:8 row_mask:0xf bank_mask:0xc
	v_mov_b32_dpp v217, v221 row_ror:8 row_mask:0xf bank_mask:0xc
	v_mov_b32_dpp v218, v244 row_ror:8 row_mask:0xf bank_mask:0x3
	v_mov_b32_dpp v219, v245 row_ror:8 row_mask:0xf bank_mask:0x3
	v_mov_b32_dpp v220, v246 row_ror:8 row_mask:0xf bank_mask:0x3
	v_mov_b32_dpp v221, v247 row_ror:8 row_mask:0xf bank_mask:0x3
	v_pk_add_f32 v[76:77], v[76:77], v[214:215]
	v_pk_add_f32 v[78:79], v[78:79], v[216:217]
	v_pk_add_f32 v[72:73], v[72:73], v[218:219]
	v_pk_add_f32 v[74:75], v[74:75], v[220:221]
	v_mul_f32_e32 v248, v76, v76
	v_fmac_f32_e32 v248, v77, v77
	v_fmac_f32_e32 v248, v78, v78
	v_fmac_f32_e32 v248, v79, v79
	v_fmac_f32_e32 v248, v72, v72
	v_fmac_f32_e32 v248, v73, v73
	v_fmac_f32_e32 v248, v74, v74
	v_fmac_f32_e32 v248, v75, v75
	v_cvt_pk_bf16_f32 v214, v76, v77
	v_cvt_pk_bf16_f32 v215, v78, v79
	v_cvt_pk_bf16_f32 v216, v72, v73
	v_cvt_pk_bf16_f32 v217, v74, v75
	v_add_u32_e32 v234, 0x18000, v187
	global_store_dwordx4 v234, v[214:217], s[26:27]
	v_mov_b32_e32 v244, v72
	v_mov_b32_e32 v245, v73
	v_mov_b32_e32 v246, v74
	v_mov_b32_e32 v247, v75
	v_mov_b32_dpp v72, v76 row_ror:8 row_mask:0xf bank_mask:0x3
	v_mov_b32_dpp v73, v77 row_ror:8 row_mask:0xf bank_mask:0x3
	v_mov_b32_dpp v74, v78 row_ror:8 row_mask:0xf bank_mask:0x3
	v_mov_b32_dpp v75, v79 row_ror:8 row_mask:0xf bank_mask:0x3
	v_mov_b32_dpp v76, v244 row_ror:8 row_mask:0xf bank_mask:0xc
; #define EPI_COL(u) (EPI_CB(u) + 8 * fq)
; DI u32x4 pack8(const float* v) { u32x4 w; w.x = pk2(v[0], v[1]); w.y = pk2(v[2], v[3]); w.z = pk2(v[4], v[5]); w.w = pk2(v[6], v[7]); return w; }
;     DI void operator()(const Acc& acc, const Unit& u, int wr, int wc, int fr, int fq) const {
;     ...
;             for (int m = 0; m < 4; ++m) {
;                 const int row = EPI_ROW(u); float part = 0.f;
; #pragma unroll
;                 for (int bj = 0; bj < 2; ++bj) {
;                     const int col = EPI_COL(u);
;                     const float* rp = res + (size_t)row * 1024 + col; float* op = out + (size_t)row * 1024 + col;
;                     const f32x4 o0 = *(const f32x4*)rp + acc[ai][bj][m][0], o1 = *(const f32x4*)(rp + 4) + acc[ai][bj][m][1];
;                     *(f32x4*)op = o0; *(f32x4*)(op + 4) = o1;
;                     part += o0[0] * o0[0] + o0[1] * o0[1] + o0[2] * o0[2] + o0[3] * o0[3] + o1[0] * o1[0] + o1[1] * o1[1] + o1[2] * o1[2] + o1[3] * o1[3];
;                     const float v[8] = {o0[0], o0[1], o0[2], o0[3], o1[0], o1[1], o1[2], o1[3]};
;                     *(u32x4*)(xb + (size_t)row * 1024 + col) = pack8(v);
;                 }
;                 part += __shfl_xor(part, 16); part += __shfl_xor(part, 32);
;                 if (fq == 0) atomicAdd(rss + row, part);
	v_mov_b32_dpp v77, v245 row_ror:8 row_mask:0xf bank_mask:0xc
	v_mov_b32_dpp v78, v246 row_ror:8 row_mask:0xf bank_mask:0xc
	v_mov_b32_dpp v79, v247 row_ror:8 row_mask:0xf bank_mask:0xc
	v_add_u32_e32 v230, 0x30000, v186
	v_add_u32_e32 v231, 0x38000, v186
	global_store_dwordx4 v230, v[76:79], s[24:25]
	global_store_dwordx4 v231, v[72:75], s[24:25]
	v_mov_b32_e32 v244, v222
	v_mov_b32_e32 v245, v223
	v_mov_b32_e32 v246, v224
	v_mov_b32_e32 v247, v225
	v_mov_b32_dpp v222, v226 row_ror:8 row_mask:0xf bank_mask:0xc
	v_mov_b32_dpp v223, v227 row_ror:8 row_mask:0xf bank_mask:0xc
	v_mov_b32_dpp v224, v228 row_ror:8 row_mask:0xf bank_mask:0xc
	v_mov_b32_dpp v225, v229 row_ror:8 row_mask:0xf bank_mask:0xc
	v_mov_b32_dpp v226, v244 row_ror:8 row_mask:0xf bank_mask:0x3
	v_mov_b32_dpp v227, v245 row_ror:8 row_mask:0xf bank_mask:0x3
	v_mov_b32_dpp v228, v246 row_ror:8 row_mask:0xf bank_mask:0x3
	v_mov_b32_dpp v229, v247 row_ror:8 row_mask:0xf bank_mask:0x3
	v_pk_add_f32 v[68:69], v[68:69], v[222:223]
	v_pk_add_f32 v[70:71], v[70:71], v[224:225]
	v_pk_add_f32 v[64:65], v[64:65], v[226:227]
	v_pk_add_f32 v[66:67], v[66:67], v[228:229]
	v_fmac_f32_e32 v248, v68, v68
	v_fmac_f32_e32 v248, v69, v69
	v_fmac_f32_e32 v248, v70, v70
	v_fmac_f32_e32 v248, v71, v71
	v_fmac_f32_e32 v248, v64, v64
	v_fmac_f32_e32 v248, v65, v65
	v_fmac_f32_e32 v248, v66, v66
	v_fmac_f32_e32 v248, v67, v67
	v_cvt_pk_bf16_f32 v222, v68, v69
	v_cvt_pk_bf16_f32 v223, v70, v71
	v_cvt_pk_bf16_f32 v224, v64, v65
	v_cvt_pk_bf16_f32 v225, v66, v67
	global_store_dwordx4 v234, v[222:225], s[26:27] offset:256
	v_mov_b32_e32 v244, v64
	v_mov_b32_e32 v245, v65
	v_mov_b32_e32 v246, v66
	v_mov_b32_e32 v247, v67
	v_mov_b32_dpp v64, v68 row_ror:8 row_mask:0xf bank_mask:0x3
	v_mov_b32_dpp v65, v69 row_ror:8 row_mask:0xf bank_mask:0x3
	v_mov_b32_dpp v66, v70 row_ror:8 row_mask:0xf bank_mask:0x3
	v_mov_b32_dpp v67, v71 row_ror:8 row_mask:0xf bank_mask:0x3
	v_mov_b32_dpp v68, v244 row_ror:8 row_mask:0xf bank_mask:0xc
	v_mov_b32_dpp v69, v245 row_ror:8 row_mask:0xf bank_mask:0xc
	v_mov_b32_dpp v70, v246 row_ror:8 row_mask:0xf bank_mask:0xc
	v_mov_b32_dpp v71, v247 row_ror:8 row_mask:0xf bank_mask:0xc
	global_store_dwordx4 v230, v[68:71], s[24:25] offset:512
	global_store_dwordx4 v231, v[64:67], s[24:25] offset:512
	ds_bpermute_b32 v244, v242, v235
	ds_bpermute_b32 v245, v242, v236
	ds_bpermute_b32 v246, v242, v237
	ds_bpermute_b32 v247, v242, v248
	s_waitcnt lgkmcnt(0)
	v_add_f32_e32 v235, v235, v244
	v_add_f32_e32 v236, v236, v245
	v_add_f32_e32 v237, v237, v246
	v_add_f32_e32 v248, v248, v247
	ds_bpermute_b32 v244, v243, v235
	ds_bpermute_b32 v245, v243, v236
	ds_bpermute_b32 v246, v243, v237
	ds_bpermute_b32 v247, v243, v248
	s_waitcnt lgkmcnt(0)
	v_add_f32_e32 v235, v235, v244
	v_add_f32_e32 v236, v236, v245
	v_add_f32_e32 v237, v237, v246
	v_add_f32_e32 v248, v248, v247
	s_and_saveexec_b64 s[6:7], vcc
	v_lshlrev_b32_e32 v234, 2, v240
	global_atomic_add_f32 v234, v235, s[38:39] offset:0
	global_atomic_add_f32 v234, v236, s[38:39] offset:64
	global_atomic_add_f32 v234, v237, s[38:39] offset:128
	global_atomic_add_f32 v234, v248, s[38:39] offset:192
	s_or_b64 exec, exec, s[6:7]
	v_add_u32_e32 v230, 0xa0000, v186
	v_add_u32_e32 v231, 0xa8000, v186
	global_load_dwordx4 v[174:177], v230, s[20:21]
	global_load_dwordx4 v[178:181], v231, s[20:21]
	global_load_dwordx4 v[182:185], v230, s[20:21] offset:512
	global_load_dwordx4 v[210:213], v231, s[20:21] offset:512
	v_add_u32_e32 v230, 0xb0000, v186
	v_add_u32_e32 v231, 0xb8000, v186
	global_load_dwordx4 v[214:217], v230, s[20:21]
	global_load_dwordx4 v[218:221], v231, s[20:21]
	global_load_dwordx4 v[222:225], v230, s[20:21] offset:512
	global_load_dwordx4 v[226:229], v231, s[20:21] offset:512
	s_waitcnt vmcnt(24)
	v_mov_b32_e32 v244, v138
	v_mov_b32_e32 v245, v139
	v_mov_b32_e32 v246, v140
	v_mov_b32_e32 v247, v141
	v_mov_b32_dpp v138, v142 row_ror:8 row_mask:0xf bank_mask:0xc
	v_mov_b32_dpp v139, v143 row_ror:8 row_mask:0xf bank_mask:0xc
	v_mov_b32_dpp v140, v144 row_ror:8 row_mask:0xf bank_mask:0xc
	v_mov_b32_dpp v141, v145 row_ror:8 row_mask:0xf bank_mask:0xc
	v_mov_b32_dpp v142, v244 row_ror:8 row_mask:0xf bank_mask:0x3
	v_mov_b32_dpp v143, v245 row_ror:8 row_mask:0xf bank_mask:0x3
	v_mov_b32_dpp v144, v246 row_ror:8 row_mask:0xf bank_mask:0x3
	v_mov_b32_dpp v145, v247 row_ror:8 row_mask:0xf bank_mask:0x3
	v_pk_add_f32 v[60:61], v[60:61], v[138:139]
	v_pk_add_f32 v[62:63], v[62:63], v[140:141]
	v_pk_add_f32 v[56:57], v[56:57], v[142:143]
	v_pk_add_f32 v[58:59], v[58:59], v[144:145]
	v_mul_f32_e32 v235, v60, v60
	v_fmac_f32_e32 v235, v61, v61
	v_fmac_f32_e32 v235, v62, v62
	v_fmac_f32_e32 v235, v63, v63
	v_fmac_f32_e32 v235, v56, v56
	v_fmac_f32_e32 v235, v57, v57
	v_fmac_f32_e32 v235, v58, v58
	v_fmac_f32_e32 v235, v59, v59
	v_cvt_pk_bf16_f32 v138, v60, v61
	v_cvt_pk_bf16_f32 v139, v62, v63
	v_cvt_pk_bf16_f32 v140, v56, v57
	v_cvt_pk_bf16_f32 v141, v58, v59
	v_add_u32_e32 v234, 0x40000, v187
	global_store_dwordx4 v234, v[138:141], s[26:27]
	v_mov_b32_e32 v244, v56
	v_mov_b32_e32 v245, v57
	v_mov_b32_e32 v246, v58
	v_mov_b32_e32 v247, v59
	v_mov_b32_dpp v56, v60 row_ror:8 row_mask:0xf bank_mask:0x3
	v_mov_b32_dpp v57, v61 row_ror:8 row_mask:0xf bank_mask:0x3
	v_mov_b32_dpp v58, v62 row_ror:8 row_mask:0xf bank_mask:0x3
	v_mov_b32_dpp v59, v63 row_ror:8 row_mask:0xf bank_mask:0x3
	v_mov_b32_dpp v60, v244 row_ror:8 row_mask:0xf bank_mask:0xc
	v_mov_b32_dpp v61, v245 row_ror:8 row_mask:0xf bank_mask:0xc
	v_mov_b32_dpp v62, v246 row_ror:8 row_mask:0xf bank_mask:0xc
	v_mov_b32_dpp v63, v247 row_ror:8 row_mask:0xf bank_mask:0xc
	v_add_u32_e32 v230, 0x80000, v186
; #define EPI_COL(u) (EPI_CB(u) + 8 * fq)
; DI u32x4 pack8(const float* v) { u32x4 w; w.x = pk2(v[0], v[1]); w.y = pk2(v[2], v[3]); w.z = pk2(v[4], v[5]); w.w = pk2(v[6], v[7]); return w; }
;     DI void operator()(const Acc& acc, const Unit& u, int wr, int wc, int fr, int fq) const {
;     ...
;             for (int m = 0; m < 4; ++m) {
;                 const int row = EPI_ROW(u); float part = 0.f;
; #pragma unroll
;                 for (int bj = 0; bj < 2; ++bj) {
;                     const int col = EPI_COL(u);
;                     const float* rp = res + (size_t)row * 1024 + col; float* op = out + (size_t)row * 1024 + col;
;                     const f32x4 o0 = *(const f32x4*)rp + acc[ai][bj][m][0], o1 = *(const f32x4*)(rp + 4) + acc[ai][bj][m][1];
;                     *(f32x4*)op = o0; *(f32x4*)(op + 4) = o1;
;                     part += o0[0] * o0[0] + o0[1] * o0[1] + o0[2] * o0[2] + o0[3] * o0[3] + o1[0] * o1[0] + o1[1] * o1[1] + o1[2] * o1[2] + o1[3] * o1[3];
;                     const float v[8] = {o0[0], o0[1], o0[2], o0[3], o1[0], o1[1], o1[2], o1[3]};
;                     *(u32x4*)(xb + (size_t)row * 1024 + col) = pack8(v);
;                 }
	v_add_u32_e32 v231, 0x88000, v186
	global_store_dwordx4 v230, v[60:63], s[24:25]
	global_store_dwordx4 v231, v[56:59], s[24:25]
	v_mov_b32_e32 v244, v150
	v_mov_b32_e32 v245, v151
	v_mov_b32_e32 v246, v152
	v_mov_b32_e32 v247, v153
	v_mov_b32_dpp v150, v154 row_ror:8 row_mask:0xf bank_mask:0xc
	v_mov_b32_dpp v151, v155 row_ror:8 row_mask:0xf bank_mask:0xc
	v_mov_b32_dpp v152, v156 row_ror:8 row_mask:0xf bank_mask:0xc
	v_mov_b32_dpp v153, v157 row_ror:8 row_mask:0xf bank_mask:0xc
	v_mov_b32_dpp v154, v244 row_ror:8 row_mask:0xf bank_mask:0x3
	v_mov_b32_dpp v155, v245 row_ror:8 row_mask:0xf bank_mask:0x3
	v_mov_b32_dpp v156, v246 row_ror:8 row_mask:0xf bank_mask:0x3
	v_mov_b32_dpp v157, v247 row_ror:8 row_mask:0xf bank_mask:0x3
	v_pk_add_f32 v[52:53], v[52:53], v[150:151]
	v_pk_add_f32 v[54:55], v[54:55], v[152:153]
	v_pk_add_f32 v[48:49], v[48:49], v[154:155]
	v_pk_add_f32 v[50:51], v[50:51], v[156:157]
	v_fmac_f32_e32 v235, v52, v52
	v_fmac_f32_e32 v235, v53, v53
	v_fmac_f32_e32 v235, v54, v54
	v_fmac_f32_e32 v235, v55, v55
	v_fmac_f32_e32 v235, v48, v48
	v_fmac_f32_e32 v235, v49, v49
	v_fmac_f32_e32 v235, v50, v50
	v_fmac_f32_e32 v235, v51, v51
	v_cvt_pk_bf16_f32 v150, v52, v53
	v_cvt_pk_bf16_f32 v151, v54, v55
	v_cvt_pk_bf16_f32 v152, v48, v49
	v_cvt_pk_bf16_f32 v153, v50, v51
	global_store_dwordx4 v234, v[150:153], s[26:27] offset:256
	v_mov_b32_e32 v244, v48
	v_mov_b32_e32 v245, v49
	v_mov_b32_e32 v246, v50
	v_mov_b32_e32 v247, v51
	v_mov_b32_dpp v48, v52 row_ror:8 row_mask:0xf bank_mask:0x3
	v_mov_b32_dpp v49, v53 row_ror:8 row_mask:0xf bank_mask:0x3
	v_mov_b32_dpp v50, v54 row_ror:8 row_mask:0xf bank_mask:0x3
	v_mov_b32_dpp v51, v55 row_ror:8 row_mask:0xf bank_mask:0x3
	v_mov_b32_dpp v52, v244 row_ror:8 row_mask:0xf bank_mask:0xc
	v_mov_b32_dpp v53, v245 row_ror:8 row_mask:0xf bank_mask:0xc
	v_mov_b32_dpp v54, v246 row_ror:8 row_mask:0xf bank_mask:0xc
	v_mov_b32_dpp v55, v247 row_ror:8 row_mask:0xf bank_mask:0xc
	global_store_dwordx4 v230, v[52:55], s[24:25] offset:512
	global_store_dwordx4 v231, v[48:51], s[24:25] offset:512
	v_mov_b32_e32 v244, v158
	v_mov_b32_e32 v245, v159
	v_mov_b32_e32 v246, v160
	v_mov_b32_e32 v247, v161
	v_mov_b32_dpp v158, v162 row_ror:8 row_mask:0xf bank_mask:0xc
	v_mov_b32_dpp v159, v163 row_ror:8 row_mask:0xf bank_mask:0xc
	v_mov_b32_dpp v160, v164 row_ror:8 row_mask:0xf bank_mask:0xc
	v_mov_b32_dpp v161, v165 row_ror:8 row_mask:0xf bank_mask:0xc
	v_mov_b32_dpp v162, v244 row_ror:8 row_mask:0xf bank_mask:0x3
	v_mov_b32_dpp v163, v245 row_ror:8 row_mask:0xf bank_mask:0x3
	v_mov_b32_dpp v164, v246 row_ror:8 row_mask:0xf bank_mask:0x3
	v_mov_b32_dpp v165, v247 row_ror:8 row_mask:0xf bank_mask:0x3
	v_pk_add_f32 v[44:45], v[44:45], v[158:159]
	v_pk_add_f32 v[46:47], v[46:47], v[160:161]
	v_pk_add_f32 v[40:41], v[40:41], v[162:163]
	v_pk_add_f32 v[42:43], v[42:43], v[164:165]
	v_mul_f32_e32 v236, v44, v44
	v_fmac_f32_e32 v236, v45, v45
	v_fmac_f32_e32 v236, v46, v46
	v_fmac_f32_e32 v236, v47, v47
	v_fmac_f32_e32 v236, v40, v40
	v_fmac_f32_e32 v236, v41, v41
	v_fmac_f32_e32 v236, v42, v42
	v_fmac_f32_e32 v236, v43, v43
	v_cvt_pk_bf16_f32 v158, v44, v45
	v_cvt_pk_bf16_f32 v159, v46, v47
	v_cvt_pk_bf16_f32 v160, v40, v41
	v_cvt_pk_bf16_f32 v161, v42, v43
	v_add_u32_e32 v234, 0x48000, v187
	global_store_dwordx4 v234, v[158:161], s[26:27]
	v_mov_b32_e32 v244, v40
	v_mov_b32_e32 v245, v41
	v_mov_b32_e32 v246, v42
	v_mov_b32_e32 v247, v43
	v_mov_b32_dpp v40, v44 row_ror:8 row_mask:0xf bank_mask:0x3
	v_mov_b32_dpp v41, v45 row_ror:8 row_mask:0xf bank_mask:0x3
	v_mov_b32_dpp v42, v46 row_ror:8 row_mask:0xf bank_mask:0x3
	v_mov_b32_dpp v43, v47 row_ror:8 row_mask:0xf bank_mask:0x3
	v_mov_b32_dpp v44, v244 row_ror:8 row_mask:0xf bank_mask:0xc
	v_mov_b32_dpp v45, v245 row_ror:8 row_mask:0xf bank_mask:0xc
	v_mov_b32_dpp v46, v246 row_ror:8 row_mask:0xf bank_mask:0xc
	v_mov_b32_dpp v47, v247 row_ror:8 row_mask:0xf bank_mask:0xc
	v_add_u32_e32 v230, 0x90000, v186
	v_add_u32_e32 v231, 0x98000, v186
	global_store_dwordx4 v230, v[44:47], s[24:25]
	global_store_dwordx4 v231, v[40:43], s[24:25]
	v_mov_b32_e32 v244, v166
	v_mov_b32_e32 v245, v167
	v_mov_b32_e32 v246, v168
	v_mov_b32_e32 v247, v169
	v_mov_b32_dpp v166, v170 row_ror:8 row_mask:0xf bank_mask:0xc
	v_mov_b32_dpp v167, v171 row_ror:8 row_mask:0xf bank_mask:0xc
	v_mov_b32_dpp v168, v172 row_ror:8 row_mask:0xf bank_mask:0xc
	v_mov_b32_dpp v169, v173 row_ror:8 row_mask:0xf bank_mask:0xc
	v_mov_b32_dpp v170, v244 row_ror:8 row_mask:0xf bank_mask:0x3
	v_mov_b32_dpp v171, v245 row_ror:8 row_mask:0xf bank_mask:0x3
	v_mov_b32_dpp v172, v246 row_ror:8 row_mask:0xf bank_mask:0x3
	v_mov_b32_dpp v173, v247 row_ror:8 row_mask:0xf bank_mask:0x3
	v_pk_add_f32 v[36:37], v[36:37], v[166:167]
	v_pk_add_f32 v[38:39], v[38:39], v[168:169]
	v_pk_add_f32 v[32:33], v[32:33], v[170:171]
	v_pk_add_f32 v[34:35], v[34:35], v[172:173]
	v_fmac_f32_e32 v236, v36, v36
	v_fmac_f32_e32 v236, v37, v37
	v_fmac_f32_e32 v236, v38, v38
	v_fmac_f32_e32 v236, v39, v39
	v_fmac_f32_e32 v236, v32, v32
	v_fmac_f32_e32 v236, v33, v33
	v_fmac_f32_e32 v236, v34, v34
	v_fmac_f32_e32 v236, v35, v35
	v_cvt_pk_bf16_f32 v166, v36, v37
	v_cvt_pk_bf16_f32 v167, v38, v39
	v_cvt_pk_bf16_f32 v168, v32, v33
	v_cvt_pk_bf16_f32 v169, v34, v35
	global_store_dwordx4 v234, v[166:169], s[26:27] offset:256
	v_mov_b32_e32 v244, v32
	v_mov_b32_e32 v245, v33
	v_mov_b32_e32 v246, v34
	v_mov_b32_e32 v247, v35
	v_mov_b32_dpp v32, v36 row_ror:8 row_mask:0xf bank_mask:0x3
	v_mov_b32_dpp v33, v37 row_ror:8 row_mask:0xf bank_mask:0x3
	v_mov_b32_dpp v34, v38 row_ror:8 row_mask:0xf bank_mask:0x3
	v_mov_b32_dpp v35, v39 row_ror:8 row_mask:0xf bank_mask:0x3
	v_mov_b32_dpp v36, v244 row_ror:8 row_mask:0xf bank_mask:0xc
	v_mov_b32_dpp v37, v245 row_ror:8 row_mask:0xf bank_mask:0xc
	v_mov_b32_dpp v38, v246 row_ror:8 row_mask:0xf bank_mask:0xc
	v_mov_b32_dpp v39, v247 row_ror:8 row_mask:0xf bank_mask:0xc
	global_store_dwordx4 v230, v[36:39], s[24:25] offset:512
	global_store_dwordx4 v231, v[32:35], s[24:25] offset:512
	s_waitcnt vmcnt(12)
; #define EPI_COL(u) (EPI_CB(u) + 8 * fq)
; DI u32x4 pack8(const float* v) { u32x4 w; w.x = pk2(v[0], v[1]); w.y = pk2(v[2], v[3]); w.z = pk2(v[4], v[5]); w.w = pk2(v[6], v[7]); return w; }
;     DI void operator()(const Acc& acc, const Unit& u, int wr, int wc, int fr, int fq) const {
;     ...
;             for (int m = 0; m < 4; ++m) {
;                 const int row = EPI_ROW(u); float part = 0.f;
; #pragma unroll
;                 for (int bj = 0; bj < 2; ++bj) {
;                     const int col = EPI_COL(u);
;                     const float* rp = res + (size_t)row * 1024 + col; float* op = out + (size_t)row * 1024 + col;
;                     const f32x4 o0 = *(const f32x4*)rp + acc[ai][bj][m][0], o1 = *(const f32x4*)(rp + 4) + acc[ai][bj][m][1];
;                     *(f32x4*)op = o0; *(f32x4*)(op + 4) = o1;
;                     part += o0[0] * o0[0] + o0[1] * o0[1] + o0[2] * o0[2] + o0[3] * o0[3] + o1[0] * o1[0] + o1[1] * o1[1] + o1[2] * o1[2] + o1[3] * o1[3];
;                     const float v[8] = {o0[0], o0[1], o0[2], o0[3], o1[0], o1[1], o1[2], o1[3]};
;                     *(u32x4*)(xb + (size_t)row * 1024 + col) = pack8(v);
;                 }
	v_mov_b32_e32 v244, v174
	v_mov_b32_e32 v245, v175
	v_mov_b32_e32 v246, v176
	v_mov_b32_e32 v247, v177
	v_mov_b32_dpp v174, v178 row_ror:8 row_mask:0xf bank_mask:0xc
	v_mov_b32_dpp v175, v179 row_ror:8 row_mask:0xf bank_mask:0xc
	v_mov_b32_dpp v176, v180 row_ror:8 row_mask:0xf bank_mask:0xc
	v_mov_b32_dpp v177, v181 row_ror:8 row_mask:0xf bank_mask:0xc
	v_mov_b32_dpp v178, v244 row_ror:8 row_mask:0xf bank_mask:0x3
	v_mov_b32_dpp v179, v245 row_ror:8 row_mask:0xf bank_mask:0x3
	v_mov_b32_dpp v180, v246 row_ror:8 row_mask:0xf bank_mask:0x3
	v_mov_b32_dpp v181, v247 row_ror:8 row_mask:0xf bank_mask:0x3
	v_pk_add_f32 v[28:29], v[28:29], v[174:175]
	v_pk_add_f32 v[30:31], v[30:31], v[176:177]
	v_pk_add_f32 v[24:25], v[24:25], v[178:179]
	v_pk_add_f32 v[26:27], v[26:27], v[180:181]
	v_mul_f32_e32 v237, v28, v28
	v_fmac_f32_e32 v237, v29, v29
	v_fmac_f32_e32 v237, v30, v30
	v_fmac_f32_e32 v237, v31, v31
	v_fmac_f32_e32 v237, v24, v24
	v_fmac_f32_e32 v237, v25, v25
	v_fmac_f32_e32 v237, v26, v26
	v_fmac_f32_e32 v237, v27, v27
	v_cvt_pk_bf16_f32 v174, v28, v29
	v_cvt_pk_bf16_f32 v175, v30, v31
	v_cvt_pk_bf16_f32 v176, v24, v25
	v_cvt_pk_bf16_f32 v177, v26, v27
	v_add_u32_e32 v234, 0x50000, v187
	global_store_dwordx4 v234, v[174:177], s[26:27]
	v_mov_b32_e32 v244, v24
	v_mov_b32_e32 v245, v25
	v_mov_b32_e32 v246, v26
	v_mov_b32_e32 v247, v27
	v_mov_b32_dpp v24, v28 row_ror:8 row_mask:0xf bank_mask:0x3
	v_mov_b32_dpp v25, v29 row_ror:8 row_mask:0xf bank_mask:0x3
	v_mov_b32_dpp v26, v30 row_ror:8 row_mask:0xf bank_mask:0x3
	v_mov_b32_dpp v27, v31 row_ror:8 row_mask:0xf bank_mask:0x3
	v_mov_b32_dpp v28, v244 row_ror:8 row_mask:0xf bank_mask:0xc
	v_mov_b32_dpp v29, v245 row_ror:8 row_mask:0xf bank_mask:0xc
	v_mov_b32_dpp v30, v246 row_ror:8 row_mask:0xf bank_mask:0xc
	v_mov_b32_dpp v31, v247 row_ror:8 row_mask:0xf bank_mask:0xc
	v_add_u32_e32 v230, 0xa0000, v186
	v_add_u32_e32 v231, 0xa8000, v186
	global_store_dwordx4 v230, v[28:31], s[24:25]
	global_store_dwordx4 v231, v[24:27], s[24:25]
	v_mov_b32_e32 v244, v182
	v_mov_b32_e32 v245, v183
	v_mov_b32_e32 v246, v184
	v_mov_b32_e32 v247, v185
	v_mov_b32_dpp v182, v210 row_ror:8 row_mask:0xf bank_mask:0xc
	v_mov_b32_dpp v183, v211 row_ror:8 row_mask:0xf bank_mask:0xc
	v_mov_b32_dpp v184, v212 row_ror:8 row_mask:0xf bank_mask:0xc
	v_mov_b32_dpp v185, v213 row_ror:8 row_mask:0xf bank_mask:0xc
	v_mov_b32_dpp v210, v244 row_ror:8 row_mask:0xf bank_mask:0x3
	v_mov_b32_dpp v211, v245 row_ror:8 row_mask:0xf bank_mask:0x3
	v_mov_b32_dpp v212, v246 row_ror:8 row_mask:0xf bank_mask:0x3
	v_mov_b32_dpp v213, v247 row_ror:8 row_mask:0xf bank_mask:0x3
	v_pk_add_f32 v[20:21], v[20:21], v[182:183]
	v_pk_add_f32 v[22:23], v[22:23], v[184:185]
	v_pk_add_f32 v[16:17], v[16:17], v[210:211]
	v_pk_add_f32 v[18:19], v[18:19], v[212:213]
	v_fmac_f32_e32 v237, v20, v20
	v_fmac_f32_e32 v237, v21, v21
	v_fmac_f32_e32 v237, v22, v22
	v_fmac_f32_e32 v237, v23, v23
	v_fmac_f32_e32 v237, v16, v16
	v_fmac_f32_e32 v237, v17, v17
	v_fmac_f32_e32 v237, v18, v18
	v_fmac_f32_e32 v237, v19, v19
	v_cvt_pk_bf16_f32 v182, v20, v21
	v_cvt_pk_bf16_f32 v183, v22, v23
	v_cvt_pk_bf16_f32 v184, v16, v17
	v_cvt_pk_bf16_f32 v185, v18, v19
	global_store_dwordx4 v234, v[182:185], s[26:27] offset:256
	v_mov_b32_e32 v244, v16
	v_mov_b32_e32 v245, v17
	v_mov_b32_e32 v246, v18
	v_mov_b32_e32 v247, v19
	v_mov_b32_dpp v16, v20 row_ror:8 row_mask:0xf bank_mask:0x3
	v_mov_b32_dpp v17, v21 row_ror:8 row_mask:0xf bank_mask:0x3
	v_mov_b32_dpp v18, v22 row_ror:8 row_mask:0xf bank_mask:0x3
	v_mov_b32_dpp v19, v23 row_ror:8 row_mask:0xf bank_mask:0x3
	v_mov_b32_dpp v20, v244 row_ror:8 row_mask:0xf bank_mask:0xc
	v_mov_b32_dpp v21, v245 row_ror:8 row_mask:0xf bank_mask:0xc
	v_mov_b32_dpp v22, v246 row_ror:8 row_mask:0xf bank_mask:0xc
	v_mov_b32_dpp v23, v247 row_ror:8 row_mask:0xf bank_mask:0xc
	global_store_dwordx4 v230, v[20:23], s[24:25] offset:512
	global_store_dwordx4 v231, v[16:19], s[24:25] offset:512
	v_mov_b32_e32 v244, v214
	v_mov_b32_e32 v245, v215
	v_mov_b32_e32 v246, v216
	v_mov_b32_e32 v247, v217
	v_mov_b32_dpp v214, v218 row_ror:8 row_mask:0xf bank_mask:0xc
	v_mov_b32_dpp v215, v219 row_ror:8 row_mask:0xf bank_mask:0xc
	v_mov_b32_dpp v216, v220 row_ror:8 row_mask:0xf bank_mask:0xc
	v_mov_b32_dpp v217, v221 row_ror:8 row_mask:0xf bank_mask:0xc
	v_mov_b32_dpp v218, v244 row_ror:8 row_mask:0xf bank_mask:0x3
; #define EPI_COL(u) (EPI_CB(u) + 8 * fq)
; DI u32x4 pack8(const float* v) { u32x4 w; w.x = pk2(v[0], v[1]); w.y = pk2(v[2], v[3]); w.z = pk2(v[4], v[5]); w.w = pk2(v[6], v[7]); return w; }
;     DI void operator()(const Acc& acc, const Unit& u, int wr, int wc, int fr, int fq) const {
;     ...
;             for (int m = 0; m < 4; ++m) {
;                 const int row = EPI_ROW(u); float part = 0.f;
; #pragma unroll
;                 for (int bj = 0; bj < 2; ++bj) {
;                     const int col = EPI_COL(u);
;                     const float* rp = res + (size_t)row * 1024 + col; float* op = out + (size_t)row * 1024 + col;
;                     const f32x4 o0 = *(const f32x4*)rp + acc[ai][bj][m][0], o1 = *(const f32x4*)(rp + 4) + acc[ai][bj][m][1];
;                     *(f32x4*)op = o0; *(f32x4*)(op + 4) = o1;
;                     part += o0[0] * o0[0] + o0[1] * o0[1] + o0[2] * o0[2] + o0[3] * o0[3] + o1[0] * o1[0] + o1[1] * o1[1] + o1[2] * o1[2] + o1[3] * o1[3];
;                     const float v[8] = {o0[0], o0[1], o0[2], o0[3], o1[0], o1[1], o1[2], o1[3]};
;                     *(u32x4*)(xb + (size_t)row * 1024 + col) = pack8(v);
;                 }
;                 part += __shfl_xor(part, 16); part += __shfl_xor(part, 32);
;                 if (fq == 0) atomicAdd(rss + row, part);
	v_mov_b32_dpp v219, v245 row_ror:8 row_mask:0xf bank_mask:0x3
	v_mov_b32_dpp v220, v246 row_ror:8 row_mask:0xf bank_mask:0x3
	v_mov_b32_dpp v221, v247 row_ror:8 row_mask:0xf bank_mask:0x3
	v_pk_add_f32 v[12:13], v[12:13], v[214:215]
	v_pk_add_f32 v[14:15], v[14:15], v[216:217]
	v_pk_add_f32 v[8:9], v[8:9], v[218:219]
	v_pk_add_f32 v[10:11], v[10:11], v[220:221]
	v_mul_f32_e32 v248, v12, v12
	v_fmac_f32_e32 v248, v13, v13
	v_fmac_f32_e32 v248, v14, v14
	v_fmac_f32_e32 v248, v15, v15
	v_fmac_f32_e32 v248, v8, v8
	v_fmac_f32_e32 v248, v9, v9
	v_fmac_f32_e32 v248, v10, v10
	v_fmac_f32_e32 v248, v11, v11
	v_cvt_pk_bf16_f32 v214, v12, v13
	v_cvt_pk_bf16_f32 v215, v14, v15
	v_cvt_pk_bf16_f32 v216, v8, v9
	v_cvt_pk_bf16_f32 v217, v10, v11
	v_add_u32_e32 v234, 0x58000, v187
	global_store_dwordx4 v234, v[214:217], s[26:27]
	v_mov_b32_e32 v244, v8
	v_mov_b32_e32 v245, v9
	v_mov_b32_e32 v246, v10
	v_mov_b32_e32 v247, v11
	v_mov_b32_dpp v8, v12 row_ror:8 row_mask:0xf bank_mask:0x3
	v_mov_b32_dpp v9, v13 row_ror:8 row_mask:0xf bank_mask:0x3
	v_mov_b32_dpp v10, v14 row_ror:8 row_mask:0xf bank_mask:0x3
	v_mov_b32_dpp v11, v15 row_ror:8 row_mask:0xf bank_mask:0x3
	v_mov_b32_dpp v12, v244 row_ror:8 row_mask:0xf bank_mask:0xc
	v_mov_b32_dpp v13, v245 row_ror:8 row_mask:0xf bank_mask:0xc
	v_mov_b32_dpp v14, v246 row_ror:8 row_mask:0xf bank_mask:0xc
	v_mov_b32_dpp v15, v247 row_ror:8 row_mask:0xf bank_mask:0xc
	v_add_u32_e32 v230, 0xb0000, v186
	v_add_u32_e32 v231, 0xb8000, v186
	global_store_dwordx4 v230, v[12:15], s[24:25]
	global_store_dwordx4 v231, v[8:11], s[24:25]
	v_mov_b32_e32 v244, v222
	v_mov_b32_e32 v245, v223
	v_mov_b32_e32 v246, v224
	v_mov_b32_e32 v247, v225
	v_mov_b32_dpp v222, v226 row_ror:8 row_mask:0xf bank_mask:0xc
	v_mov_b32_dpp v223, v227 row_ror:8 row_mask:0xf bank_mask:0xc
	v_mov_b32_dpp v224, v228 row_ror:8 row_mask:0xf bank_mask:0xc
	v_mov_b32_dpp v225, v229 row_ror:8 row_mask:0xf bank_mask:0xc
	v_mov_b32_dpp v226, v244 row_ror:8 row_mask:0xf bank_mask:0x3
	v_mov_b32_dpp v227, v245 row_ror:8 row_mask:0xf bank_mask:0x3
	v_mov_b32_dpp v228, v246 row_ror:8 row_mask:0xf bank_mask:0x3
	v_mov_b32_dpp v229, v247 row_ror:8 row_mask:0xf bank_mask:0x3
	v_pk_add_f32 v[4:5], v[4:5], v[222:223]
	v_pk_add_f32 v[6:7], v[6:7], v[224:225]
	v_pk_add_f32 v[0:1], v[0:1], v[226:227]
	v_pk_add_f32 v[2:3], v[2:3], v[228:229]
	v_fmac_f32_e32 v248, v4, v4
	v_fmac_f32_e32 v248, v5, v5
	v_fmac_f32_e32 v248, v6, v6
	v_fmac_f32_e32 v248, v7, v7
	v_fmac_f32_e32 v248, v0, v0
	v_fmac_f32_e32 v248, v1, v1
	v_fmac_f32_e32 v248, v2, v2
	v_fmac_f32_e32 v248, v3, v3
	v_cvt_pk_bf16_f32 v222, v4, v5
	v_cvt_pk_bf16_f32 v223, v6, v7
	v_cvt_pk_bf16_f32 v224, v0, v1
	v_cvt_pk_bf16_f32 v225, v2, v3
	global_store_dwordx4 v234, v[222:225], s[26:27] offset:256
	v_mov_b32_e32 v244, v0
	v_mov_b32_e32 v245, v1
	v_mov_b32_e32 v246, v2
	v_mov_b32_e32 v247, v3
	v_mov_b32_dpp v0, v4 row_ror:8 row_mask:0xf bank_mask:0x3
	v_mov_b32_dpp v1, v5 row_ror:8 row_mask:0xf bank_mask:0x3
	v_mov_b32_dpp v2, v6 row_ror:8 row_mask:0xf bank_mask:0x3
	v_mov_b32_dpp v3, v7 row_ror:8 row_mask:0xf bank_mask:0x3
	v_mov_b32_dpp v4, v244 row_ror:8 row_mask:0xf bank_mask:0xc
	v_mov_b32_dpp v5, v245 row_ror:8 row_mask:0xf bank_mask:0xc
	v_mov_b32_dpp v6, v246 row_ror:8 row_mask:0xf bank_mask:0xc
	v_mov_b32_dpp v7, v247 row_ror:8 row_mask:0xf bank_mask:0xc
	global_store_dwordx4 v230, v[4:7], s[24:25] offset:512
	global_store_dwordx4 v231, v[0:3], s[24:25] offset:512
	ds_bpermute_b32 v244, v242, v235
	ds_bpermute_b32 v245, v242, v236
	ds_bpermute_b32 v246, v242, v237
	ds_bpermute_b32 v247, v242, v248
	s_waitcnt lgkmcnt(0)
	v_add_f32_e32 v235, v235, v244
	v_add_f32_e32 v236, v236, v245
	v_add_f32_e32 v237, v237, v246
	v_add_f32_e32 v248, v248, v247
	ds_bpermute_b32 v244, v243, v235
	ds_bpermute_b32 v245, v243, v236
	ds_bpermute_b32 v246, v243, v237
	ds_bpermute_b32 v247, v243, v248
	s_waitcnt lgkmcnt(0)
	v_add_f32_e32 v235, v235, v244
	v_add_f32_e32 v236, v236, v245
	v_add_f32_e32 v237, v237, v246
	v_add_f32_e32 v248, v248, v247
	s_and_saveexec_b64 s[6:7], vcc
	v_lshlrev_b32_e32 v234, 2, v240
	global_atomic_add_f32 v234, v235, s[38:39] offset:512
	global_atomic_add_f32 v234, v236, s[38:39] offset:576
	global_atomic_add_f32 v234, v237, s[38:39] offset:640
	global_atomic_add_f32 v234, v248, s[38:39] offset:704
	s_or_b64 exec, exec, s[6:7]
	s_mov_b64 s[6:7], exec
